# NSA selected branch: hand-written software-pipelined tile block for non-diagonal tiles (permlane max reduce, deferred l reduce, skip O rescale when max unchanged)
# speedup vs baseline: 1.0131x; 1.0130x over previous
.LBB0_105:
	v_readfirstlane_b32 s11, v88
	v_readfirstlane_b32 s12, v144
	s_lshr_b32 s12, s12, 6
	s_cmp_lt_u32 s11, s12
	s_cbranch_scc1 .Lself_fast
	v_mov_b32_e32 v64, v185
	v_mov_b32_e32 v65, v184
	v_mov_b32_e32 v66, v187
	v_mov_b32_e32 v67, v186
	s_nop 1
	v_permlane16_swap_b32_e32 v185, v64
	v_permlane16_swap_b32_e32 v184, v65
	v_permlane16_swap_b32_e32 v187, v66
	v_permlane16_swap_b32_e32 v186, v67
	v_add_f32_e32 v185, v185, v64
	v_add_f32_e32 v184, v184, v65
	v_add_f32_e32 v187, v187, v66
	v_add_f32_e32 v186, v186, v67
	v_mov_b32_e32 v64, v185
	v_mov_b32_e32 v65, v184
	v_mov_b32_e32 v66, v187
	v_mov_b32_e32 v67, v186
	s_nop 1
	v_permlane32_swap_b32_e32 v185, v64
	v_permlane32_swap_b32_e32 v184, v65
	v_permlane32_swap_b32_e32 v187, v66
	v_permlane32_swap_b32_e32 v186, v67
	v_add_f32_e32 v185, v185, v64
	v_add_f32_e32 v184, v184, v65
	v_add_f32_e32 v187, v187, v66
	v_add_f32_e32 v186, v186, v67
	v_add_u32_e32 v94, s10, v208
	v_add_u32_e32 v151, v94, v149
	ds_read_b128 v[76:79], v151
	v_add_u32_e32 v192, v147, v149
	ds_read_b128 v[64:67], v192 offset:32768
	ds_read_b128 v[84:87], v151 offset:2048
	v_add_u32_e32 v196, v94, v155
	v_add_u32_e32 v193, v147, v155
	ds_read_b128 v[72:75], v192 offset:40960
	ds_read_b128 v[132:135], v196
	ds_read_b128 v[128:131], v196 offset:2048
	ds_read_b128 v[80:83], v193 offset:32768
	ds_read_b128 v[68:71], v193 offset:40960
	s_waitcnt lgkmcnt(0)
	v_mfma_f32_16x16x32_bf16 v[96:99], v[76:79], v[64:67], 0
	v_lshl_or_b32 v194, v88, 6, v145
	v_lshrrev_b64 v[88:89], v88, v[172:173]
	v_and_b32_e32 v88, 1, v88
	v_mfma_f32_16x16x32_bf16 v[104:107], v[84:87], v[64:67], 0
	v_mov_b32_e32 v89, v153
	v_cmp_gt_i32_e64 s[8:9], v194, v144
	v_cmp_eq_u64_e32 vcc, 0, v[88:89]
	v_mfma_f32_16x16x32_bf16 v[96:99], v[132:135], v[80:83], v[96:99]
	s_or_b64 s[22:23], vcc, s[8:9]
	v_or_b32_e32 v95, 2, v194
	v_cmp_lt_i32_e64 s[20:21], v194, v144
	v_mfma_f32_16x16x32_bf16 v[104:107], v[128:131], v[80:83], v[104:107]
	v_cmp_gt_i32_e64 s[8:9], v95, v144
	s_nop 2
	v_cndmask_b32_e64 v89, v96, v204, s[22:23]
	v_or_b32_e32 v96, 3, v194
	v_cndmask_b32_e64 v92, v204, v97, s[20:21]
	s_or_b64 s[24:25], vcc, s[8:9]
	v_cmp_gt_i32_e64 s[8:9], v96, v144
	v_or_b32_e32 v97, 16, v194
	v_cndmask_b32_e64 v95, v98, v204, s[24:25]
	s_or_b64 s[26:27], vcc, s[8:9]
	v_cmp_gt_i32_e64 s[8:9], v97, v144
	v_or_b32_e32 v98, 17, v194
	v_cndmask_b32_e64 v96, v99, v204, s[26:27]
	s_or_b64 s[28:29], vcc, s[8:9]
	v_cmp_gt_i32_e64 s[8:9], v98, v144
	v_or_b32_e32 v99, 18, v194
	v_cndmask_b32_e32 v88, v92, v204, vcc
	v_cndmask_b32_e64 v97, v104, v204, s[28:29]
	s_or_b64 s[30:31], vcc, s[8:9]
	v_cmp_gt_i32_e64 s[8:9], v99, v144
	v_or_b32_e32 v104, 19, v194
	v_max3_f32 v92, v89, s75, v88
	s_or_b64 s[34:35], vcc, s[8:9]
	v_cmp_gt_i32_e64 s[8:9], v104, v144
	v_max3_f32 v92, v92, v95, v96
	v_cndmask_b32_e64 v98, v105, v204, s[30:31]
	s_or_b64 s[36:37], vcc, s[8:9]
	v_max3_f32 v92, v92, v97, v98
	v_cndmask_b32_e64 v99, v106, v204, s[34:35]
	v_cndmask_b32_e64 v116, v107, v204, s[36:37]
	v_add_u32_e32 v91, v94, v211
	v_max3_f32 v92, v92, v99, v116
	ds_read2st64_b64 v[100:103], v91 offset0:16 offset1:20
	ds_bpermute_b32 v104, v157, v92
	v_add_u32_e32 v93, s10, v209
	v_add_u32_e32 v90, v94, v210
	v_add_u32_e32 v105, v93, v210
	s_waitcnt lgkmcnt(1)
	v_mov_b32_e32 v122, v100
	s_waitcnt lgkmcnt(0)
	v_max_f32_e32 v100, v104, v104
	v_max_f32_e32 v92, v92, v100
	ds_bpermute_b32 v104, v159, v92
	v_add_u32_e32 v106, v93, v211
	ds_read2st64_b64 v[108:111], v90 offset0:16 offset1:20
	v_mov_b32_e32 v123, v101
	v_add_u32_e32 v225, v94, v213
	s_waitcnt lgkmcnt(1)
	v_max3_f32 v197, v223, v92, v104
	v_sub_f32_e32 v89, v89, v197
	v_exp_f32_e32 v89, v89
	v_sub_f32_e32 v88, v88, v197
	v_exp_f32_e32 v88, v88
	ds_read_b64 v[112:113], v90 offset:12288
	ds_read_b64 v[114:115], v91 offset:12288
	ds_read_b64 v[104:105], v105 offset:8192
	ds_read_b64 v[106:107], v106 offset:8192
	v_add_f32_e32 v91, 0, v89
	v_sub_f32_e32 v90, v223, v197
	v_add_f32_e32 v189, v88, v91
	v_sub_f32_e32 v91, v95, v197
	v_exp_f32_e32 v117, v91
	v_sub_f32_e32 v91, v96, v197
	v_exp_f32_e32 v190, v90
	v_exp_f32_e32 v119, v91
	v_sub_f32_e32 v91, v97, v197
	v_exp_f32_e32 v125, v91
	v_sub_f32_e32 v91, v98, v197
	v_exp_f32_e32 v127, v91
	v_sub_f32_e32 v91, v99, v197
	v_sub_f32_e32 v90, v116, v197
	s_waitcnt lgkmcnt(4)
	v_mov_b32_e32 v121, v109
	v_mov_b32_e32 v101, v111
	v_exp_f32_e32 v109, v91
	v_exp_f32_e32 v111, v90
	v_cvt_pk_bf16_f32 v92, v89, v88
	v_pk_mul_f32 v[90:91], v[58:59], v[190:191] op_sel_hi:[1,0]
	v_pk_mul_f32 v[88:89], v[56:57], v[190:191] op_sel_hi:[1,0]
	v_pk_mul_f32 v[58:59], v[50:51], v[190:191] op_sel_hi:[1,0]
	v_pk_mul_f32 v[56:57], v[48:49], v[190:191] op_sel_hi:[1,0]
	v_mfma_f32_16x16x32_bf16 v[48:51], v[76:79], v[72:75], 0
	v_mul_f32_e64 v98, v62, v190
	v_mul_f32_e64 v99, v63, v190
	v_pk_mul_f32 v[96:97], v[60:61], v[190:191] op_sel_hi:[1,0]
	v_pk_mul_f32 v[62:63], v[54:55], v[190:191] op_sel_hi:[1,0]
	v_pk_mul_f32 v[60:61], v[52:53], v[190:191] op_sel_hi:[1,0]
	v_mfma_f32_16x16x32_bf16 v[52:55], v[84:87], v[72:75], 0
	v_add_u32_e32 v223, v94, v212
	v_mov_b32_e32 v120, v108
	v_mov_b32_e32 v100, v110
	v_mfma_f32_16x16x32_bf16 v[48:51], v[132:135], v[68:71], v[48:51]
	v_add_u32_e32 v227, v93, v212
	v_add_u32_e32 v228, v93, v213
	v_or_b32_e32 v93, 32, v194
	v_mfma_f32_16x16x32_bf16 v[52:55], v[128:131], v[68:71], v[52:55]
	v_cmp_gt_i32_e64 s[10:11], v93, v144
	s_nop 2
	v_cndmask_b32_e64 v49, v204, v49, s[20:21]
	v_cndmask_b32_e64 v48, v48, v204, s[22:23]
	v_cndmask_b32_e32 v49, v49, v204, vcc
	v_max3_f32 v94, v48, s75, v49
	v_cndmask_b32_e64 v50, v50, v204, s[24:25]
	v_cndmask_b32_e64 v51, v51, v204, s[26:27]
	v_max3_f32 v94, v94, v50, v51
	v_cndmask_b32_e64 v108, v52, v204, s[28:29]
	v_cndmask_b32_e64 v110, v53, v204, s[30:31]
	v_max3_f32 v52, v94, v108, v110
	v_cndmask_b32_e64 v226, v54, v204, s[34:35]
	v_cndmask_b32_e64 v229, v55, v204, s[36:37]
	v_max3_f32 v52, v52, v226, v229
	ds_bpermute_b32 v53, v157, v52
	v_or_b32_e32 v93, 33, v194
	v_cmp_gt_i32_e64 s[8:9], v93, v144
	v_or_b32_e32 v93, 34, v194
	v_or_b32_e32 v54, 48, v194
	s_waitcnt lgkmcnt(0)
	v_max_f32_e32 v53, v53, v53
	v_max_f32_e32 v52, v52, v53
	ds_bpermute_b32 v53, v159, v52
	v_cmp_gt_i32_e64 s[12:13], v93, v144
	v_or_b32_e32 v93, 35, v194
	v_cmp_gt_i32_e64 s[14:15], v54, v144
	v_or_b32_e32 v54, 49, v194
	s_waitcnt lgkmcnt(0)
	v_max3_f32 v224, v222, v52, v53
	v_sub_f32_e32 v48, v48, v224
	v_exp_f32_e32 v232, v48
	v_sub_f32_e32 v48, v49, v224
	v_exp_f32_e32 v233, v48
	v_sub_f32_e32 v48, v50, v224
	v_exp_f32_e32 v116, v48
	v_add_f32_e32 v48, 0, v232
	v_add_f32_e32 v188, v233, v48
	v_sub_f32_e32 v48, v51, v224
	v_exp_f32_e32 v118, v48
	v_sub_f32_e32 v48, v108, v224
	v_exp_f32_e32 v124, v48
	v_pk_add_f32 v[52:53], v[116:117], v[188:189]
	v_cmp_gt_i32_e64 s[16:17], v93, v144
	v_cmp_gt_i32_e64 s[18:19], v54, v144
	v_cvt_pk_bf16_f32 v93, v117, v119
	v_cvt_pk_bf16_f32 v94, v125, v127
	v_cvt_pk_bf16_f32 v95, v109, v111
	v_sub_f32_e32 v54, v110, v224
	v_mfma_f32_16x16x32_bf16 v[48:51], v[120:123], v[92:95], v[96:99]
	v_exp_f32_e32 v126, v54
	v_or_b32_e32 v195, 50, v194
	v_cmp_gt_i32_e64 s[38:39], v195, v144
	v_pk_add_f32 v[96:97], v[118:119], v[52:53]
	v_mfma_f32_16x16x32_bf16 v[52:55], v[100:103], v[92:95], v[88:91]
	v_mov_b32_e32 v189, v190
	s_or_b64 s[10:11], vcc, s[10:11]
	s_or_b64 s[8:9], vcc, s[8:9]
	v_pk_add_f32 v[88:89], v[124:125], v[96:97]
	v_sub_f32_e32 v96, v226, v224
	v_exp_f32_e32 v108, v96
	ds_read_b128 v[96:99], v192 offset:49152
	v_pk_add_f32 v[230:231], v[126:127], v[88:89]
	v_mfma_f32_16x16x32_bf16 v[88:91], v[112:115], v[92:95], v[60:63]
	s_or_b64 s[12:13], vcc, s[12:13]
	s_or_b64 s[16:17], vcc, s[16:17]
	s_or_b64 s[14:15], vcc, s[14:15]
	v_sub_f32_e32 v60, v229, v224
	v_mfma_f32_16x16x32_bf16 v[92:95], v[104:107], v[92:95], v[56:59]
	v_cvt_pk_bf16_f32 v58, v124, v126
	ds_read_b128 v[124:127], v193 offset:49152
	v_exp_f32_e32 v110, v60
	v_cvt_pk_bf16_f32 v57, v116, v118
	v_pk_add_f32 v[60:61], v[108:109], v[230:231]
	v_sub_f32_e32 v56, v222, v224
	v_exp_f32_e32 v188, v56
	v_cvt_pk_bf16_f32 v56, v232, v233
	ds_read_b128 v[116:119], v192 offset:57344
	s_waitcnt lgkmcnt(2)
	v_mfma_f32_16x16x32_bf16 v[230:233], v[76:79], v[96:99], 0
	v_cvt_pk_bf16_f32 v59, v108, v110
	v_add_f32_e64 v60, v110, v60
	v_add_f32_e64 v61, v111, v61
	v_or_b32_e32 v222, 51, v194
	v_mfma_f32_16x16x32_bf16 v[234:237], v[84:87], v[96:99], 0
	ds_read_b128 v[108:111], v193 offset:57344
	v_pk_mul_f32 v[46:47], v[46:47], v[188:189] op_sel_hi:[1,0]
	v_pk_mul_f32 v[44:45], v[44:45], v[188:189] op_sel_hi:[1,0]
	s_waitcnt lgkmcnt(2)
	v_mfma_f32_16x16x32_bf16 v[192:195], v[132:135], v[124:127], v[230:233]
	v_mul_f32_e64 v30, v30, v188
	v_mul_f32_e64 v31, v31, v188
	v_pk_mul_f32 v[28:29], v[28:29], v[188:189] op_sel_hi:[1,0]
	v_pk_mul_f32 v[34:35], v[34:35], v[188:189] op_sel_hi:[1,0]
	v_mfma_f32_16x16x32_bf16 v[230:233], v[128:131], v[124:127], v[234:237]
	v_mul_f32_e64 v32, v32, v188
	v_mul_f32_e64 v33, v33, v188
	s_nop 0
	v_cndmask_b32_e64 v190, v192, v204, s[22:23]
	v_cndmask_b32_e64 v192, v204, v193, s[20:21]
	v_cndmask_b32_e32 v192, v192, v204, vcc
	v_max3_f32 v193, v190, s75, v192
	v_cndmask_b32_e64 v194, v194, v204, s[24:25]
	v_cndmask_b32_e64 v195, v195, v204, s[26:27]
	v_max3_f32 v193, v193, v194, v195
	v_cndmask_b32_e64 v226, v230, v204, s[28:29]
	v_cndmask_b32_e64 v230, v231, v204, s[30:31]
	v_max3_f32 v193, v193, v226, v230
	v_cndmask_b32_e64 v232, v232, v204, s[34:35]
	v_cndmask_b32_e64 v233, v233, v204, s[36:37]
	v_max3_f32 v193, v193, v232, v233
	ds_bpermute_b32 v229, v157, v193
	s_waitcnt lgkmcnt(2)
	v_mfma_f32_16x16x32_bf16 v[76:79], v[76:79], v[116:119], 0
	v_mul_f32_e64 v26, v26, v188
	v_mul_f32_e64 v27, v27, v188
	v_pk_mul_f32 v[24:25], v[24:25], v[188:189] op_sel_hi:[1,0]
	ds_bpermute_b32 v63, v157, v61
	s_waitcnt lgkmcnt(1)
	v_max_f32_e32 v229, v229, v229
	v_max_f32_e32 v193, v193, v229
	ds_bpermute_b32 v229, v159, v193
	v_mfma_f32_16x16x32_bf16 v[44:47], v[120:123], v[56:59], v[44:47]
	ds_bpermute_b32 v62, v157, v60
	s_or_b64 s[18:19], vcc, s[18:19]
	s_waitcnt lgkmcnt(1)
	v_max3_f32 v229, v191, v193, v229
	v_mfma_f32_16x16x32_bf16 v[28:31], v[100:103], v[56:59], v[28:31]
	v_sub_f32_e32 v190, v190, v229
	v_exp_f32_e32 v190, v190
	v_sub_f32_e32 v192, v192, v229
	v_mfma_f32_16x16x32_bf16 v[32:35], v[112:115], v[56:59], v[32:35]
	v_exp_f32_e32 v192, v192
	s_waitcnt lgkmcnt(0)
	v_pk_add_f32 v[60:61], v[60:61], v[62:63]
	ds_bpermute_b32 v63, v159, v61
	v_mfma_f32_16x16x32_bf16 v[24:27], v[104:107], v[56:59], v[24:27]
	v_sub_f32_e32 v58, v195, v229
	v_exp_f32_e32 v59, v58
	v_sub_f32_e32 v58, v226, v229
	v_mfma_f32_16x16x32_bf16 v[84:87], v[84:87], v[116:119], 0
	v_sub_f32_e32 v56, v191, v229
	v_exp_f32_e32 v191, v58
	v_sub_f32_e32 v58, v230, v229
	v_mfma_f32_16x16x32_bf16 v[76:79], v[132:135], v[108:111], v[76:79]
	v_exp_f32_e32 v193, v58
	v_sub_f32_e32 v58, v232, v229
	v_exp_f32_e32 v195, v58
	v_sub_f32_e32 v58, v233, v229
	v_mfma_f32_16x16x32_bf16 v[84:87], v[128:131], v[108:111], v[84:87]
	v_exp_f32_e32 v233, v58
	s_nop 1
	v_cndmask_b32_e64 v58, v204, v77, s[20:21]
	v_exp_f32_e32 v234, v56
	v_cndmask_b32_e64 v56, v76, v204, s[22:23]
	v_cndmask_b32_e32 v58, v58, v204, vcc
	v_max3_f32 v76, v56, s75, v58
	v_cndmask_b32_e64 v128, v78, v204, s[24:25]
	v_cndmask_b32_e64 v129, v79, v204, s[26:27]
	v_add_f32_e32 v57, 0, v190
	v_max3_f32 v76, v76, v128, v129
	v_cndmask_b32_e64 v130, v84, v204, s[28:29]
	v_cndmask_b32_e64 v131, v85, v204, s[30:31]
	v_add_f32_e32 v231, v192, v57
	v_sub_f32_e32 v57, v194, v229
	v_max3_f32 v76, v76, v130, v131
	v_cndmask_b32_e64 v194, v86, v204, s[34:35]
	v_cndmask_b32_e64 v232, v87, v204, s[36:37]
	v_max3_f32 v76, v76, v194, v232
	ds_bpermute_b32 v77, v157, v76
	v_pk_mul_f32 v[84:85], v[16:17], v[234:235] op_sel_hi:[1,0]
	v_pk_mul_f32 v[42:43], v[42:43], v[234:235] op_sel_hi:[1,0]
	v_pk_mul_f32 v[40:41], v[40:41], v[234:235] op_sel_hi:[1,0]
	v_pk_mul_f32 v[38:39], v[38:39], v[234:235] op_sel_hi:[1,0]
	s_waitcnt lgkmcnt(0)
	v_max_f32_e32 v77, v77, v77
	v_max_f32_e32 v133, v76, v77
	ds_bpermute_b32 v134, v159, v133
	v_pk_mul_f32 v[36:37], v[36:37], v[234:235] op_sel_hi:[1,0]
	v_pk_mul_f32 v[78:79], v[22:23], v[234:235] op_sel_hi:[1,0]
	v_pk_mul_f32 v[76:77], v[20:21], v[234:235] op_sel_hi:[1,0]
	v_pk_mul_f32 v[86:87], v[18:19], v[234:235] op_sel_hi:[1,0]
	s_waitcnt lgkmcnt(0)
	v_max3_f32 v226, v171, v133, v134
	v_sub_f32_e32 v16, v56, v226
	v_exp_f32_e32 v235, v16
	v_sub_f32_e32 v17, v58, v226
	v_exp_f32_e32 v236, v17
	v_sub_f32_e32 v17, v128, v226
	v_exp_f32_e32 v57, v57
	v_exp_f32_e32 v56, v17
	v_sub_f32_e32 v17, v129, v226
	v_exp_f32_e32 v58, v17
	v_sub_f32_e32 v17, v130, v226
	v_cvt_pk_bf16_f32 v132, v190, v192
	v_add_f32_e32 v16, 0, v235
	v_exp_f32_e32 v190, v17
	v_add_f32_e32 v230, v236, v16
	v_pk_add_f32 v[16:17], v[56:57], v[230:231]
	v_sub_f32_e32 v20, v131, v226
	v_pk_add_f32 v[16:17], v[58:59], v[16:17]
	v_cvt_pk_bf16_f32 v133, v57, v59
	v_cvt_pk_bf16_f32 v134, v191, v193
	v_cvt_pk_bf16_f32 v135, v195, v233
	v_exp_f32_e32 v192, v20
	v_pk_add_f32 v[128:129], v[190:191], v[16:17]
	v_mfma_f32_16x16x32_bf16 v[16:19], v[120:123], v[132:135], v[40:43]
	ds_bpermute_b32 v62, v159, v60
	v_cmp_gt_i32_e64 s[22:23], v222, v144
	s_or_b64 s[20:21], vcc, s[38:39]
	v_sub_f32_e32 v40, v194, v226
	v_mfma_f32_16x16x32_bf16 v[20:23], v[100:103], v[132:135], v[36:39]
	v_exp_f32_e32 v194, v40
	ds_read_b128 v[40:43], v151 offset:4096
	v_cvt_pk_bf16_f32 v38, v190, v192
	v_mfma_f32_16x16x32_bf16 v[76:79], v[112:115], v[132:135], v[76:79]
	v_sub_f32_e32 v36, v232, v226
	v_exp_f32_e32 v232, v36
	v_pk_add_f32 v[36:37], v[192:193], v[128:129]
	v_mov_b32_e32 v129, v234
	v_pk_add_f32 v[36:37], v[194:195], v[36:37]
	v_cvt_pk_bf16_f32 v39, v194, v232
	v_mfma_f32_16x16x32_bf16 v[84:87], v[104:107], v[132:135], v[84:87]
	v_add_f32_e64 v230, v232, v36
	v_add_f32_e64 v231, v233, v37
	v_sub_f32_e32 v36, v171, v226
	v_exp_f32_e32 v128, v36
	v_cvt_pk_bf16_f32 v36, v235, v236
	v_cvt_pk_bf16_f32 v37, v56, v58
	s_waitcnt lgkmcnt(1)
	v_pk_add_f32 v[130:131], v[60:61], v[62:63]
	v_pk_mul_f32 v[14:15], v[14:15], v[128:129] op_sel_hi:[1,0]
	v_pk_mul_f32 v[12:13], v[12:13], v[128:129] op_sel_hi:[1,0]
	v_pk_mul_f32 v[6:7], v[6:7], v[128:129] op_sel_hi:[1,0]
	v_pk_mul_f32 v[4:5], v[4:5], v[128:129] op_sel_hi:[1,0]
	v_mfma_f32_16x16x32_bf16 v[12:15], v[120:123], v[36:39], v[12:15]
	ds_bpermute_b32 v121, v157, v231
	ds_bpermute_b32 v120, v157, v230
	v_pk_mul_f32 v[10:11], v[10:11], v[128:129] op_sel_hi:[1,0]
	v_mfma_f32_16x16x32_bf16 v[4:7], v[112:115], v[36:39], v[4:7]
	ds_read_b128 v[112:115], v151 offset:6144
	v_pk_mul_f32 v[8:9], v[8:9], v[128:129] op_sel_hi:[1,0]
	v_pk_mul_f32 v[2:3], v[2:3], v[128:129] op_sel_hi:[1,0]
	v_pk_mul_f32 v[0:1], v[0:1], v[128:129] op_sel_hi:[1,0]
	v_mfma_f32_16x16x32_bf16 v[8:11], v[100:103], v[36:39], v[8:11]
	s_waitcnt lgkmcnt(1)
	v_pk_add_f32 v[132:133], v[230:231], v[120:121]
	ds_read_b128 v[120:123], v196 offset:6144
	s_or_b64 vcc, vcc, s[22:23]
	v_mfma_f32_16x16x32_bf16 v[0:3], v[104:107], v[36:39], v[0:3]
	ds_read_b128 v[36:39], v196 offset:4096
	ds_read2st64_b64 v[102:105], v223 offset0:16 offset1:20
	ds_bpermute_b32 v135, v159, v133
	v_mfma_f32_16x16x32_bf16 v[56:59], v[40:43], v[64:67], 0
	ds_bpermute_b32 v134, v159, v132
	s_waitcnt lgkmcnt(2)
	v_mov_b32_e32 v100, v102
	v_mfma_f32_16x16x32_bf16 v[60:63], v[112:115], v[64:67], 0
	ds_read2st64_b64 v[64:67], v225 offset0:16 offset1:20
	v_mov_b32_e32 v101, v103
	s_waitcnt lgkmcnt(0)
	v_mov_b32_e32 v102, v64
	v_mfma_f32_16x16x32_bf16 v[56:59], v[36:39], v[80:83], v[56:59]
	v_mov_b32_e32 v103, v65
	v_mov_b32_e32 v64, v104
	v_mov_b32_e32 v65, v105
	v_mfma_f32_16x16x32_bf16 v[60:63], v[120:123], v[80:83], v[60:63]
	ds_read_b64 v[104:105], v223 offset:12288
	ds_read_b64 v[106:107], v225 offset:12288
	ds_read_b64 v[80:81], v227 offset:8192
	ds_read_b64 v[82:83], v228 offset:8192
	v_cndmask_b32_e64 v56, v56, v204, s[10:11]
	v_cndmask_b32_e64 v151, v57, v204, s[8:9]
	v_max3_f32 v57, v56, s75, v151
	v_cndmask_b32_e64 v171, v58, v204, s[12:13]
	v_cndmask_b32_e64 v190, v59, v204, s[16:17]
	v_max3_f32 v57, v57, v171, v190
	v_cndmask_b32_e64 v192, v60, v204, s[14:15]
	v_cndmask_b32_e64 v194, v61, v204, s[18:19]
	v_max3_f32 v57, v57, v192, v194
	v_cndmask_b32_e64 v196, v62, v204, s[20:21]
	v_cndmask_b32_e32 v222, v63, v204, vcc
	v_max3_f32 v57, v57, v196, v222
	ds_bpermute_b32 v58, v157, v57
	s_waitcnt lgkmcnt(0)
	s_waitcnt vmcnt(0)
	s_barrier
	v_max_f32_e32 v58, v58, v58
	v_max_f32_e32 v57, v57, v58
	ds_bpermute_b32 v58, v159, v57
	s_waitcnt lgkmcnt(0)
	v_max3_f32 v223, v197, v57, v58
	v_sub_f32_e32 v56, v56, v223
	v_exp_f32_e32 v191, v56
	v_mfma_f32_16x16x32_bf16 v[56:59], v[40:43], v[72:75], 0
	v_sub_f32_e32 v60, v151, v223
	v_sub_f32_e32 v225, v197, v223
	v_exp_f32_e32 v197, v60
	v_mfma_f32_16x16x32_bf16 v[60:63], v[112:115], v[72:75], 0
	v_sub_f32_e32 v72, v190, v223
	v_exp_f32_e32 v73, v72
	v_sub_f32_e32 v72, v192, v223
	v_mfma_f32_16x16x32_bf16 v[56:59], v[36:39], v[68:71], v[56:59]
	v_exp_f32_e32 v193, v72
	v_sub_f32_e32 v72, v194, v223
	v_exp_f32_e32 v235, v72
	v_mfma_f32_16x16x32_bf16 v[60:63], v[120:123], v[68:71], v[60:63]
	v_sub_f32_e32 v70, v196, v223
	s_nop 2
	v_cndmask_b32_e64 v56, v56, v204, s[10:11]
	v_cndmask_b32_e64 v57, v57, v204, s[8:9]
	v_max3_f32 v68, v56, s75, v57
	v_cndmask_b32_e64 v58, v58, v204, s[12:13]
	v_cndmask_b32_e64 v59, v59, v204, s[16:17]
	v_max3_f32 v68, v68, v58, v59
	v_cndmask_b32_e64 v60, v60, v204, s[14:15]
	v_cndmask_b32_e64 v61, v61, v204, s[18:19]
	v_max3_f32 v68, v68, v60, v61
	v_cndmask_b32_e64 v62, v62, v204, s[20:21]
	v_cndmask_b32_e32 v63, v63, v204, vcc
	v_max3_f32 v68, v68, v62, v63
	ds_bpermute_b32 v69, v157, v68
	v_exp_f32_e32 v71, v70
	v_sub_f32_e32 v70, v222, v223
	v_sub_f32_e32 v151, v171, v223
	v_exp_f32_e32 v195, v151
	s_waitcnt lgkmcnt(0)
	v_max_f32_e32 v69, v69, v69
	v_max_f32_e32 v68, v68, v69
	ds_bpermute_b32 v72, v159, v68
	v_exp_f32_e32 v69, v225
	v_exp_f32_e32 v75, v70
	v_cvt_pk_bf16_f32 v230, v191, v197
	v_cvt_pk_bf16_f32 v231, v195, v73
	s_waitcnt lgkmcnt(0)
	v_max3_f32 v222, v224, v68, v72
	v_sub_f32_e32 v56, v56, v222
	v_exp_f32_e32 v190, v56
	v_sub_f32_e32 v56, v57, v222
	v_exp_f32_e32 v196, v56
	v_mov_b32_e32 v228, v69
	v_pk_add_f32 v[56:57], v[190:191], 0 op_sel_hi:[1,0]
	v_pk_mul_f32 v[50:51], v[50:51], v[228:229] op_sel_hi:[1,0]
	v_pk_add_f32 v[236:237], v[196:197], v[56:57]
	v_sub_f32_e32 v56, v58, v222
	v_exp_f32_e32 v194, v56
	v_sub_f32_e32 v56, v59, v222
	v_exp_f32_e32 v72, v56
	v_sub_f32_e32 v56, v60, v222
	v_exp_f32_e32 v192, v56
	v_sub_f32_e32 v56, v61, v222
	v_exp_f32_e32 v234, v56
	v_sub_f32_e32 v56, v62, v222
	v_pk_mul_f32 v[48:49], v[48:49], v[228:229] op_sel_hi:[1,0]
	v_cvt_pk_bf16_f32 v232, v193, v235
	v_cvt_pk_bf16_f32 v233, v71, v75
	v_exp_f32_e32 v70, v56
	v_sub_f32_e32 v56, v63, v222
	v_mfma_f32_16x16x32_bf16 v[60:63], v[100:103], v[230:233], v[48:51]
	v_exp_f32_e32 v74, v56
	v_sub_f32_e32 v68, v224, v222
	v_exp_f32_e32 v68, v68
	v_pk_mul_f32 v[50:51], v[54:55], v[228:229] op_sel_hi:[1,0]
	v_pk_mul_f32 v[48:49], v[52:53], v[228:229] op_sel_hi:[1,0]
	v_pk_mul_f32 v[46:47], v[46:47], v[68:69] op_sel_hi:[1,0]
	s_nop 0
	v_mfma_f32_16x16x32_bf16 v[56:59], v[64:67], v[230:233], v[48:51]
	v_mul_f32_e64 v44, v44, v68
	v_mul_f32_e64 v45, v45, v68
	v_pk_mul_f32 v[30:31], v[30:31], v[68:69] op_sel_hi:[1,0]
	v_pk_mul_f32 v[28:29], v[28:29], v[68:69] op_sel_hi:[1,0]
	v_pk_mul_f32 v[50:51], v[90:91], v[228:229] op_sel_hi:[1,0]
	v_pk_mul_f32 v[48:49], v[88:89], v[228:229] op_sel_hi:[1,0]
	v_cvt_pk_bf16_f32 v89, v194, v72
	v_cvt_pk_bf16_f32 v91, v70, v74
	v_cvt_pk_bf16_f32 v88, v190, v196
	v_pk_mul_f32 v[34:35], v[34:35], v[68:69] op_sel_hi:[1,0]
	v_pk_mul_f32 v[32:33], v[32:33], v[68:69] op_sel_hi:[1,0]
	v_mfma_f32_16x16x32_bf16 v[52:55], v[104:107], v[230:233], v[48:51]
	v_mul_f32_e64 v26, v26, v68
	v_mul_f32_e64 v27, v27, v68
	v_pk_mul_f32 v[24:25], v[24:25], v[68:69] op_sel_hi:[1,0]
	v_cvt_pk_bf16_f32 v90, v192, v234
	v_pk_mul_f32 v[48:49], v[92:93], v[228:229] op_sel_hi:[1,0]
	v_pk_add_f32 v[92:93], v[194:195], v[236:237]
	v_pk_mul_f32 v[50:51], v[94:95], v[228:229] op_sel_hi:[1,0]
	v_pk_add_f32 v[72:73], v[72:73], v[92:93]
	v_mfma_f32_16x16x32_bf16 v[92:95], v[40:43], v[96:99], 0
	v_add_f32_e64 v72, v192, v72
	v_add_f32_e64 v73, v193, v73
	v_pk_add_f32 v[72:73], v[234:235], v[72:73]
	v_mfma_f32_16x16x32_bf16 v[96:99], v[112:115], v[96:99], 0
	v_add_f32_e64 v70, v70, v72
	v_add_f32_e64 v71, v71, v73
	v_pk_fma_f32 v[72:73], v[184:185], v[188:189], v[130:131]
	v_pk_add_f32 v[74:75], v[74:75], v[70:71]
	v_mfma_f32_16x16x32_bf16 v[92:95], v[36:39], v[124:127], v[92:95]
	ds_bpermute_b32 v191, v157, v75
	ds_bpermute_b32 v190, v157, v74
	v_pk_add_f32 v[70:71], v[132:133], v[134:135]
	v_mfma_f32_16x16x32_bf16 v[96:99], v[120:123], v[124:127], v[96:99]
	v_fma_f32 v70, v186, v128, v70
	v_fma_f32 v71, v187, v129, v71
	s_nop 1
	v_cndmask_b32_e64 v92, v92, v204, s[10:11]
	v_cndmask_b32_e64 v93, v93, v204, s[8:9]
	v_max3_f32 v124, v92, s75, v93
	v_cndmask_b32_e64 v125, v94, v204, s[12:13]
	v_cndmask_b32_e64 v126, v95, v204, s[16:17]
	v_max3_f32 v94, v124, v125, v126
	v_cndmask_b32_e64 v124, v96, v204, s[14:15]
	v_cndmask_b32_e64 v127, v97, v204, s[18:19]
	v_max3_f32 v94, v94, v124, v127
	v_cndmask_b32_e64 v98, v98, v204, s[20:21]
	v_cndmask_b32_e32 v130, v99, v204, vcc
	v_max3_f32 v94, v94, v98, v130
	ds_bpermute_b32 v95, v157, v94
	v_mfma_f32_16x16x32_bf16 v[40:43], v[40:43], v[116:119], 0
	s_waitcnt lgkmcnt(1)
	v_pk_add_f32 v[74:75], v[74:75], v[190:191]
	ds_bpermute_b32 v129, v159, v75
	ds_bpermute_b32 v128, v159, v74
	s_waitcnt lgkmcnt(2)
	v_max_f32_e32 v95, v95, v95
	v_max_f32_e32 v94, v94, v95
	ds_bpermute_b32 v95, v159, v94
	v_mfma_f32_16x16x32_bf16 v[36:39], v[36:39], v[108:111], v[40:43]
	s_waitcnt lgkmcnt(1)
	v_pk_add_f32 v[74:75], v[74:75], v[128:129]
	s_waitcnt lgkmcnt(0)
	v_max3_f32 v191, v229, v94, v95
	v_mfma_f32_16x16x32_bf16 v[94:97], v[112:115], v[116:119], 0
	v_sub_f32_e32 v40, v126, v191
	v_exp_f32_e32 v99, v40
	s_nop 0
	v_cndmask_b32_e64 v36, v36, v204, s[10:11]
	v_mfma_f32_16x16x32_bf16 v[40:43], v[120:123], v[108:111], v[94:97]
	v_cndmask_b32_e64 v37, v37, v204, s[8:9]
	v_cndmask_b32_e64 v38, v38, v204, s[12:13]
	v_cndmask_b32_e64 v39, v39, v204, s[16:17]
	v_mfma_f32_16x16x32_bf16 v[44:47], v[100:103], v[88:91], v[44:47]
	v_fma_f32 v184, v72, v68, v74
	v_fma_f32 v185, v73, v69, v75
	s_nop 1
	v_cndmask_b32_e64 v40, v40, v204, s[14:15]
	v_cndmask_b32_e64 v41, v41, v204, s[18:19]
	v_mfma_f32_16x16x32_bf16 v[28:31], v[64:67], v[88:91], v[28:31]
	v_cndmask_b32_e64 v42, v42, v204, s[20:21]
	v_cndmask_b32_e32 v43, v43, v204, vcc
	s_andn2_b64 vcc, exec, s[4:5]
	v_mfma_f32_16x16x32_bf16 v[32:35], v[104:107], v[88:91], v[32:35]
	v_mfma_f32_16x16x32_bf16 v[24:27], v[80:83], v[88:91], v[24:27]
	v_sub_f32_e32 v89, v92, v191
	v_max3_f32 v92, v36, s75, v37
	v_max3_f32 v92, v92, v38, v39
	v_max3_f32 v92, v92, v40, v41
	v_max3_f32 v92, v92, v42, v43
	ds_bpermute_b32 v94, v157, v92
	v_sub_f32_e32 v90, v93, v191
	v_exp_f32_e32 v91, v90
	v_sub_f32_e32 v90, v125, v191
	v_exp_f32_e32 v93, v90
	s_waitcnt lgkmcnt(0)
	v_max_f32_e32 v94, v94, v94
	v_max_f32_e32 v92, v92, v94
	ds_bpermute_b32 v94, v159, v92
	v_sub_f32_e32 v90, v124, v191
	v_exp_f32_e32 v109, v90
	v_sub_f32_e32 v90, v127, v191
	v_sub_f32_e32 v88, v229, v191
	s_waitcnt lgkmcnt(0)
	v_max3_f32 v171, v226, v92, v94
	v_exp_f32_e32 v111, v90
	v_sub_f32_e32 v90, v98, v191
	v_sub_f32_e32 v36, v36, v171
	v_exp_f32_e32 v89, v89
	v_exp_f32_e32 v113, v90
	v_sub_f32_e32 v90, v130, v191
	v_exp_f32_e32 v117, v88
	v_exp_f32_e32 v88, v36
	v_sub_f32_e32 v36, v37, v171
	v_exp_f32_e32 v115, v90
	v_exp_f32_e32 v90, v36
	v_sub_f32_e32 v36, v38, v171
	v_exp_f32_e32 v92, v36
	v_sub_f32_e32 v36, v39, v171
	v_exp_f32_e32 v98, v36
	v_sub_f32_e32 v38, v40, v171
	v_pk_add_f32 v[36:37], v[88:89], 0 op_sel_hi:[1,0]
	v_exp_f32_e32 v108, v38
	v_sub_f32_e32 v38, v41, v171
	v_pk_add_f32 v[36:37], v[90:91], v[36:37]
	v_exp_f32_e32 v110, v38
	v_sub_f32_e32 v38, v42, v171
	v_pk_add_f32 v[36:37], v[92:93], v[36:37]
	v_exp_f32_e32 v112, v38
	v_sub_f32_e32 v38, v43, v171
	v_pk_add_f32 v[36:37], v[98:99], v[36:37]
	v_exp_f32_e32 v114, v38
	v_pk_add_f32 v[36:37], v[108:109], v[36:37]
	v_cvt_pk_bf16_f32 v94, v89, v91
	v_sub_f32_e32 v89, v226, v171
	v_pk_add_f32 v[36:37], v[110:111], v[36:37]
	v_mov_b32_e32 v122, v117
	v_pk_add_f32 v[36:37], v[112:113], v[36:37]
	v_exp_f32_e32 v116, v89
	v_pk_add_f32 v[36:37], v[114:115], v[36:37]
	ds_bpermute_b32 v39, v157, v37
	ds_bpermute_b32 v38, v157, v36
	v_pk_mul_f32 v[18:19], v[18:19], v[122:123] op_sel_hi:[1,0]
	v_pk_mul_f32 v[16:17], v[16:17], v[122:123] op_sel_hi:[1,0]
	v_cvt_pk_bf16_f32 v95, v93, v99
	v_cvt_pk_bf16_f32 v96, v109, v111
	s_waitcnt lgkmcnt(0)
	v_pk_add_f32 v[118:119], v[36:37], v[38:39]
	ds_bpermute_b32 v121, v159, v119
	ds_bpermute_b32 v120, v159, v118
	v_cvt_pk_bf16_f32 v97, v113, v115
	v_pk_mul_f32 v[14:15], v[14:15], v[116:117] op_sel_hi:[1,0]
	v_mfma_f32_16x16x32_bf16 v[40:43], v[100:103], v[94:97], v[16:19]
	v_mul_f32_e64 v12, v12, v116
	v_mul_f32_e64 v13, v13, v116
	v_pk_mul_f32 v[10:11], v[10:11], v[116:117] op_sel_hi:[1,0]
	v_pk_mul_f32 v[8:9], v[8:9], v[116:117] op_sel_hi:[1,0]
	v_pk_mul_f32 v[18:19], v[22:23], v[122:123] op_sel_hi:[1,0]
	v_pk_mul_f32 v[16:17], v[20:21], v[122:123] op_sel_hi:[1,0]
	v_pk_mul_f32 v[6:7], v[6:7], v[116:117] op_sel_hi:[1,0]
	v_pk_mul_f32 v[4:5], v[4:5], v[116:117] op_sel_hi:[1,0]
	v_mfma_f32_16x16x32_bf16 v[36:39], v[64:67], v[94:97], v[16:19]
	v_mul_f32_e64 v2, v2, v116
	v_mul_f32_e64 v3, v3, v116
	v_pk_mul_f32 v[0:1], v[0:1], v[116:117] op_sel_hi:[1,0]
	v_pk_mul_f32 v[18:19], v[78:79], v[122:123] op_sel_hi:[1,0]
	v_pk_mul_f32 v[16:17], v[76:77], v[122:123] op_sel_hi:[1,0]
	v_mfma_f32_16x16x32_bf16 v[48:51], v[80:83], v[230:233], v[48:51]
	v_cvt_pk_bf16_f32 v76, v88, v90
	v_cvt_pk_bf16_f32 v77, v92, v98
	v_cvt_pk_bf16_f32 v78, v108, v110
	v_cvt_pk_bf16_f32 v79, v112, v114
	s_nop 0
	v_mfma_f32_16x16x32_bf16 v[20:23], v[104:107], v[94:97], v[16:19]
	s_nop 2
	v_mul_f32_e64 v18, v86, v122
	v_mul_f32_e64 v19, v87, v122
	v_pk_mul_f32 v[16:17], v[84:85], v[122:123] op_sel_hi:[1,0]
	v_mfma_f32_16x16x32_bf16 v[12:15], v[100:103], v[76:79], v[12:15]
	s_nop 0
	v_mfma_f32_16x16x32_bf16 v[16:19], v[80:83], v[94:97], v[16:19]
	v_mfma_f32_16x16x32_bf16 v[8:11], v[64:67], v[76:79], v[8:11]
	s_waitcnt lgkmcnt(0)
	v_pk_add_f32 v[64:65], v[118:119], v[120:121]
	s_nop 0
	v_pk_fma_f32 v[186:187], v[70:71], v[116:117], v[64:65]
	v_mfma_f32_16x16x32_bf16 v[4:7], v[104:107], v[76:79], v[4:7]
	v_cndmask_b32_e64 v64, 0, 1, s[6:7]
	s_nop 0
	v_readfirstlane_b32 s6, v64
	v_mfma_f32_16x16x32_bf16 v[0:3], v[80:83], v[76:79], v[0:3]
	s_xor_b32 s42, s42, s6
	s_cbranch_vccz .LBB0_107
.Lself_latch:
	v_mov_b32_e32 v88, v161
	v_mov_b64_e32 v[64:65], v[182:183]
	s_branch .LBB0_101
.Lself_fast:
	v_add_u32_e32 v134, s10, v208
	v_add_u32_e32 v194, v134, v149
	v_add_u32_e32 v195, v134, v155
	v_add_u32_e32 v254, v147, v149
	v_add_u32_e32 v255, v147, v155
	v_add_u32_e32 v196, v134, v210
	v_add_u32_e32 v197, v134, v211
	v_add_u32_e32 v236, v134, v212
	v_add_u32_e32 v237, v134, v213
	ds_read_b128 v[64:67], v194
	ds_read_b128 v[68:71], v194 offset:2048
	ds_read_b128 v[72:75], v195
	ds_read_b128 v[76:79], v195 offset:2048
	ds_read_b128 v[98:101], v254 offset:32768
	ds_read_b128 v[102:105], v255 offset:32768
	ds_read_b128 v[106:109], v254 offset:40960
	ds_read_b128 v[110:113], v255 offset:40960
	ds_read_b64 v[80:81], v196 offset:8192
	ds_read_b64 v[82:83], v197 offset:8192
	ds_read_b64 v[84:85], v196 offset:10240
	ds_read_b64 v[86:87], v197 offset:10240
	ds_read_b64 v[90:91], v196 offset:12288
	ds_read_b64 v[92:93], v197 offset:12288
	ds_read_b64 v[94:95], v196 offset:14336
	ds_read_b64 v[96:97], v197 offset:14336
	v_lshrrev_b64 v[134:135], v88, v[172:173]
	v_and_b32_e32 v134, 1, v134
	v_cmp_eq_u32_e64 s[20:21], 1, v134
	s_nop 1
	v_cndmask_b32_e64 v89, v204, 0, s[20:21]
	s_waitcnt lgkmcnt(8)
	v_mfma_f32_16x16x32_bf16 v[114:117], v[64:67], v[98:101], 0
	v_mfma_f32_16x16x32_bf16 v[118:121], v[68:71], v[98:101], 0
	v_mfma_f32_16x16x32_bf16 v[122:125], v[64:67], v[106:109], 0
	v_mfma_f32_16x16x32_bf16 v[126:129], v[68:71], v[106:109], 0
	v_mfma_f32_16x16x32_bf16 v[114:117], v[72:75], v[102:105], v[114:117]
	v_mfma_f32_16x16x32_bf16 v[118:121], v[76:79], v[102:105], v[118:121]
	v_mfma_f32_16x16x32_bf16 v[122:125], v[72:75], v[110:113], v[122:125]
	v_mfma_f32_16x16x32_bf16 v[126:129], v[76:79], v[110:113], v[126:129]
	ds_read_b128 v[98:101], v254 offset:49152
	ds_read_b128 v[102:105], v255 offset:49152
	ds_read_b128 v[106:109], v254 offset:57344
	ds_read_b128 v[110:113], v255 offset:57344
	s_waitcnt lgkmcnt(0)
	v_mfma_f32_16x16x32_bf16 v[224:227], v[64:67], v[98:101], 0
	v_max3_f32 v134, v114, s75, v115
	v_max3_f32 v134, v134, v116, v117
	v_max3_f32 v134, v134, v118, v119
	v_max3_f32 v134, v134, v120, v121
	v_max3_f32 v135, v122, s75, v123
	v_max3_f32 v135, v135, v124, v125
	v_max3_f32 v135, v135, v126, v127
	v_max3_f32 v135, v135, v128, v129
	v_add_f32_e32 v134, v134, v89
	v_add_f32_e32 v135, v135, v89
	v_mov_b32_e32 v188, v134
	v_mov_b32_e32 v189, v135
	s_nop 1
	v_permlane16_swap_b32_e32 v134, v188
	v_permlane16_swap_b32_e32 v135, v189
	v_max_f32_e32 v134, v134, v188
	v_max_f32_e32 v135, v135, v189
	v_mov_b32_e32 v188, v134
	v_mov_b32_e32 v189, v135
	s_nop 1
	v_permlane32_swap_b32_e32 v134, v188
	v_permlane32_swap_b32_e32 v135, v189
	v_mfma_f32_16x16x32_bf16 v[228:231], v[68:71], v[98:101], 0
	v_max3_f32 v134, v223, v134, v188
	v_sub_f32_e32 v190, v223, v134
	v_sub_f32_e32 v192, v134, v89
	v_exp_f32_e32 v190, v190
	v_mov_b32_e32 v223, v134
	v_max3_f32 v135, v222, v135, v189
	v_sub_f32_e32 v151, v222, v135
	v_sub_f32_e32 v193, v135, v89
	v_exp_f32_e32 v151, v151
	v_mov_b32_e32 v222, v135
	v_mfma_f32_16x16x32_bf16 v[232:235], v[64:67], v[106:109], 0
	v_sub_f32_e32 v114, v114, v192
	v_sub_f32_e32 v115, v115, v192
	v_sub_f32_e32 v116, v116, v192
	v_sub_f32_e32 v117, v117, v192
	v_sub_f32_e32 v118, v118, v192
	v_sub_f32_e32 v119, v119, v192
	v_sub_f32_e32 v120, v120, v192
	v_sub_f32_e32 v121, v121, v192
	v_sub_f32_e32 v122, v122, v193
	v_sub_f32_e32 v123, v123, v193
	v_mfma_f32_16x16x32_bf16 v[130:133], v[68:71], v[106:109], 0
	v_sub_f32_e32 v124, v124, v193
	v_sub_f32_e32 v125, v125, v193
	v_sub_f32_e32 v126, v126, v193
	v_sub_f32_e32 v127, v127, v193
	v_sub_f32_e32 v128, v128, v193
	v_sub_f32_e32 v129, v129, v193
	v_exp_f32_e32 v114, v114
	v_exp_f32_e32 v115, v115
	v_exp_f32_e32 v116, v116
	v_mfma_f32_16x16x32_bf16 v[224:227], v[72:75], v[102:105], v[224:227]
	v_exp_f32_e32 v117, v117
	v_exp_f32_e32 v118, v118
	v_exp_f32_e32 v119, v119
	v_exp_f32_e32 v120, v120
	v_exp_f32_e32 v121, v121
	v_exp_f32_e32 v122, v122
	v_exp_f32_e32 v123, v123
	v_exp_f32_e32 v124, v124
	v_exp_f32_e32 v125, v125
	v_exp_f32_e32 v126, v126
	v_mfma_f32_16x16x32_bf16 v[228:231], v[76:79], v[102:105], v[228:231]
	v_exp_f32_e32 v127, v127
	v_exp_f32_e32 v128, v128
	v_exp_f32_e32 v129, v129
	v_add_f32_e32 v134, v114, v115
	v_add_f32_e32 v188, v116, v117
	v_add_f32_e32 v134, v134, v188
	v_add_f32_e32 v188, v118, v119
	v_add_f32_e32 v134, v134, v188
	v_add_f32_e32 v188, v120, v121
	v_add_f32_e32 v134, v134, v188
	v_mfma_f32_16x16x32_bf16 v[232:235], v[72:75], v[110:113], v[232:235]
	v_fma_f32 v185, v185, v190, v134
	v_add_f32_e32 v135, v122, v123
	v_add_f32_e32 v189, v124, v125
	v_add_f32_e32 v135, v135, v189
	v_add_f32_e32 v189, v126, v127
	v_add_f32_e32 v135, v135, v189
	v_add_f32_e32 v189, v128, v129
	v_add_f32_e32 v135, v135, v189
	v_fma_f32 v184, v184, v151, v135
	v_cvt_pk_bf16_f32 v114, v114, v115
	v_mfma_f32_16x16x32_bf16 v[130:133], v[76:79], v[110:113], v[130:133]
	ds_read_b128 v[64:67], v194 offset:4096
	ds_read_b128 v[68:71], v194 offset:6144
	ds_read_b128 v[72:75], v195 offset:4096
	ds_read_b128 v[76:79], v195 offset:6144
	ds_read_b128 v[98:101], v254 offset:32768
	ds_read_b128 v[102:105], v255 offset:32768
	ds_read_b128 v[106:109], v254 offset:40960
	ds_read_b128 v[110:113], v255 offset:40960
	v_cvt_pk_bf16_f32 v115, v116, v117
	v_cvt_pk_bf16_f32 v116, v118, v119
	v_cvt_pk_bf16_f32 v117, v120, v121
	v_cvt_pk_bf16_f32 v122, v122, v123
	v_cvt_pk_bf16_f32 v123, v124, v125
	v_cvt_pk_bf16_f32 v124, v126, v127
	v_cvt_pk_bf16_f32 v125, v128, v129
	v_cmp_neq_f32_e32 vcc, 1.0, v190
	s_nop 1
	s_cbranch_vccz .Lself_r0
	v_mul_f32_e32 v60, v60, v190
	v_mul_f32_e32 v61, v61, v190
	v_mul_f32_e32 v62, v62, v190
	v_mul_f32_e32 v63, v63, v190
	v_mul_f32_e32 v56, v56, v190
	v_mul_f32_e32 v57, v57, v190
	v_mul_f32_e32 v58, v58, v190
	v_mul_f32_e32 v59, v59, v190
	v_mul_f32_e32 v52, v52, v190
	v_mul_f32_e32 v53, v53, v190
	v_mul_f32_e32 v54, v54, v190
	v_mul_f32_e32 v55, v55, v190
	v_mul_f32_e32 v48, v48, v190
	v_mul_f32_e32 v49, v49, v190
	v_mul_f32_e32 v50, v50, v190
	v_mul_f32_e32 v51, v51, v190
.Lself_r0:
	v_cmp_neq_f32_e32 vcc, 1.0, v151
	s_nop 1
	s_cbranch_vccz .Lself_r1
	v_mul_f32_e32 v44, v44, v151
	v_mul_f32_e32 v45, v45, v151
	v_mul_f32_e32 v46, v46, v151
	v_mul_f32_e32 v47, v47, v151
	v_mul_f32_e32 v28, v28, v151
	v_mul_f32_e32 v29, v29, v151
	v_mul_f32_e32 v30, v30, v151
	v_mul_f32_e32 v31, v31, v151
	v_mul_f32_e32 v32, v32, v151
	v_mul_f32_e32 v33, v33, v151
	v_mul_f32_e32 v34, v34, v151
	v_mul_f32_e32 v35, v35, v151
	v_mul_f32_e32 v24, v24, v151
	v_mul_f32_e32 v25, v25, v151
	v_mul_f32_e32 v26, v26, v151
	v_mul_f32_e32 v27, v27, v151
.Lself_r1:
	s_waitcnt lgkmcnt(12)
	v_mfma_f32_16x16x32_bf16 v[60:63], v[80:83], v[114:117], v[60:63]
	v_max3_f32 v134, v224, s75, v225
	v_max3_f32 v134, v134, v226, v227
	v_max3_f32 v134, v134, v228, v229
	v_max3_f32 v134, v134, v230, v231
	v_max3_f32 v135, v232, s75, v233
	v_mfma_f32_16x16x32_bf16 v[44:47], v[80:83], v[122:125], v[44:47]
	v_max3_f32 v135, v135, v234, v235
	v_max3_f32 v135, v135, v130, v131
	v_max3_f32 v135, v135, v132, v133
	v_add_f32_e32 v134, v134, v89
	v_add_f32_e32 v135, v135, v89
	v_mov_b32_e32 v188, v134
	v_mov_b32_e32 v189, v135
	s_nop 1
	v_permlane16_swap_b32_e32 v134, v188
	v_permlane16_swap_b32_e32 v135, v189
	v_max_f32_e32 v134, v134, v188
	v_max_f32_e32 v135, v135, v189
	v_mov_b32_e32 v188, v134
	v_mov_b32_e32 v189, v135
	s_nop 1
	v_permlane32_swap_b32_e32 v134, v188
	v_permlane32_swap_b32_e32 v135, v189
	v_mfma_f32_16x16x32_bf16 v[56:59], v[84:87], v[114:117], v[56:59]
	v_max3_f32 v134, v191, v134, v188
	v_sub_f32_e32 v190, v191, v134
	v_sub_f32_e32 v192, v134, v89
	v_exp_f32_e32 v190, v190
	v_mov_b32_e32 v191, v134
	v_mfma_f32_16x16x32_bf16 v[28:31], v[84:87], v[122:125], v[28:31]
	v_max3_f32 v135, v171, v135, v189
	v_sub_f32_e32 v151, v171, v135
	v_sub_f32_e32 v193, v135, v89
	v_exp_f32_e32 v151, v151
	v_mov_b32_e32 v171, v135
	v_mfma_f32_16x16x32_bf16 v[52:55], v[90:93], v[114:117], v[52:55]
	v_sub_f32_e32 v224, v224, v192
	v_sub_f32_e32 v225, v225, v192
	v_sub_f32_e32 v226, v226, v192
	v_sub_f32_e32 v227, v227, v192
	v_sub_f32_e32 v228, v228, v192
	v_mfma_f32_16x16x32_bf16 v[32:35], v[90:93], v[122:125], v[32:35]
	v_sub_f32_e32 v229, v229, v192
	v_sub_f32_e32 v230, v230, v192
	v_sub_f32_e32 v231, v231, v192
	v_sub_f32_e32 v232, v232, v193
	v_sub_f32_e32 v233, v233, v193
	v_mfma_f32_16x16x32_bf16 v[48:51], v[94:97], v[114:117], v[48:51]
	v_sub_f32_e32 v234, v234, v193
	v_sub_f32_e32 v235, v235, v193
	v_sub_f32_e32 v130, v130, v193
	v_sub_f32_e32 v131, v131, v193
	v_sub_f32_e32 v132, v132, v193
	v_mfma_f32_16x16x32_bf16 v[24:27], v[94:97], v[122:125], v[24:27]
	v_sub_f32_e32 v133, v133, v193
	v_exp_f32_e32 v224, v224
	v_exp_f32_e32 v225, v225
	v_exp_f32_e32 v226, v226
	s_waitcnt lgkmcnt(0)
	v_mfma_f32_16x16x32_bf16 v[114:117], v[64:67], v[98:101], 0
	v_exp_f32_e32 v227, v227
	v_exp_f32_e32 v228, v228
	v_exp_f32_e32 v229, v229
	v_exp_f32_e32 v230, v230
	v_exp_f32_e32 v231, v231
	v_mfma_f32_16x16x32_bf16 v[118:121], v[68:71], v[98:101], 0
	v_exp_f32_e32 v232, v232
	v_exp_f32_e32 v233, v233
	v_exp_f32_e32 v234, v234
	v_exp_f32_e32 v235, v235
	v_exp_f32_e32 v130, v130
	v_mfma_f32_16x16x32_bf16 v[122:125], v[64:67], v[106:109], 0
	v_exp_f32_e32 v131, v131
	v_exp_f32_e32 v132, v132
	v_exp_f32_e32 v133, v133
	v_add_f32_e32 v134, v224, v225
	v_add_f32_e32 v188, v226, v227
	v_mfma_f32_16x16x32_bf16 v[126:129], v[68:71], v[106:109], 0
	v_add_f32_e32 v134, v134, v188
	v_add_f32_e32 v188, v228, v229
	v_add_f32_e32 v134, v134, v188
	v_add_f32_e32 v188, v230, v231
	v_add_f32_e32 v134, v134, v188
	v_mfma_f32_16x16x32_bf16 v[114:117], v[72:75], v[102:105], v[114:117]
	v_fma_f32 v187, v187, v190, v134
	v_add_f32_e32 v135, v232, v233
	v_add_f32_e32 v189, v234, v235
	v_add_f32_e32 v135, v135, v189
	v_add_f32_e32 v189, v130, v131
	v_mfma_f32_16x16x32_bf16 v[118:121], v[76:79], v[102:105], v[118:121]
	v_add_f32_e32 v135, v135, v189
	v_add_f32_e32 v189, v132, v133
	v_add_f32_e32 v135, v135, v189
	v_fma_f32 v186, v186, v151, v135
	v_cvt_pk_bf16_f32 v224, v224, v225
	v_mfma_f32_16x16x32_bf16 v[122:125], v[72:75], v[110:113], v[122:125]
	v_cvt_pk_bf16_f32 v225, v226, v227
	v_cvt_pk_bf16_f32 v226, v228, v229
	v_cvt_pk_bf16_f32 v227, v230, v231
	v_cvt_pk_bf16_f32 v232, v232, v233
	v_cvt_pk_bf16_f32 v233, v234, v235
	v_mfma_f32_16x16x32_bf16 v[126:129], v[76:79], v[110:113], v[126:129]
	ds_read_b128 v[98:101], v254 offset:49152
	ds_read_b128 v[102:105], v255 offset:49152
	ds_read_b128 v[106:109], v254 offset:57344
	ds_read_b128 v[110:113], v255 offset:57344
	v_cvt_pk_bf16_f32 v234, v130, v131
	v_cvt_pk_bf16_f32 v235, v132, v133
	v_cmp_neq_f32_e32 vcc, 1.0, v190
	s_nop 1
	s_cbranch_vccz .Lself_r2
	v_mul_f32_e32 v40, v40, v190
	v_mul_f32_e32 v41, v41, v190
	v_mul_f32_e32 v42, v42, v190
	v_mul_f32_e32 v43, v43, v190
	v_mul_f32_e32 v36, v36, v190
	v_mul_f32_e32 v37, v37, v190
	v_mul_f32_e32 v38, v38, v190
	v_mul_f32_e32 v39, v39, v190
	v_mul_f32_e32 v20, v20, v190
	v_mul_f32_e32 v21, v21, v190
	v_mul_f32_e32 v22, v22, v190
	v_mul_f32_e32 v23, v23, v190
	v_mul_f32_e32 v16, v16, v190
	v_mul_f32_e32 v17, v17, v190
	v_mul_f32_e32 v18, v18, v190
	v_mul_f32_e32 v19, v19, v190
.Lself_r2:
	v_cmp_neq_f32_e32 vcc, 1.0, v151
	s_nop 1
	s_cbranch_vccz .Lself_r3
	v_mul_f32_e32 v12, v12, v151
	v_mul_f32_e32 v13, v13, v151
	v_mul_f32_e32 v14, v14, v151
	v_mul_f32_e32 v15, v15, v151
	v_mul_f32_e32 v8, v8, v151
	v_mul_f32_e32 v9, v9, v151
	v_mul_f32_e32 v10, v10, v151
	v_mul_f32_e32 v11, v11, v151
	v_mul_f32_e32 v4, v4, v151
	v_mul_f32_e32 v5, v5, v151
	v_mul_f32_e32 v6, v6, v151
	v_mul_f32_e32 v7, v7, v151
	v_mul_f32_e32 v0, v0, v151
	v_mul_f32_e32 v1, v1, v151
	v_mul_f32_e32 v2, v2, v151
	v_mul_f32_e32 v3, v3, v151
.Lself_r3:
	v_mfma_f32_16x16x32_bf16 v[40:43], v[80:83], v[224:227], v[40:43]
	v_max3_f32 v134, v114, s75, v115
	v_max3_f32 v134, v134, v116, v117
	v_max3_f32 v134, v134, v118, v119
	v_max3_f32 v134, v134, v120, v121
	v_max3_f32 v135, v122, s75, v123
	v_mfma_f32_16x16x32_bf16 v[12:15], v[80:83], v[232:235], v[12:15]
	v_max3_f32 v135, v135, v124, v125
	v_max3_f32 v135, v135, v126, v127
	v_max3_f32 v135, v135, v128, v129
	v_add_f32_e32 v134, v134, v89
	v_add_f32_e32 v135, v135, v89
	v_mov_b32_e32 v188, v134
	v_mov_b32_e32 v189, v135
	s_nop 1
	v_permlane16_swap_b32_e32 v134, v188
	v_permlane16_swap_b32_e32 v135, v189
	v_max_f32_e32 v134, v134, v188
	v_max_f32_e32 v135, v135, v189
	v_mov_b32_e32 v188, v134
	v_mov_b32_e32 v189, v135
	s_nop 1
	v_permlane32_swap_b32_e32 v134, v188
	v_permlane32_swap_b32_e32 v135, v189
	v_mfma_f32_16x16x32_bf16 v[36:39], v[84:87], v[224:227], v[36:39]
	v_max3_f32 v134, v223, v134, v188
	v_sub_f32_e32 v190, v223, v134
	v_sub_f32_e32 v192, v134, v89
	v_exp_f32_e32 v190, v190
	v_mov_b32_e32 v223, v134
	v_mfma_f32_16x16x32_bf16 v[8:11], v[84:87], v[232:235], v[8:11]
	v_max3_f32 v135, v222, v135, v189
	v_sub_f32_e32 v151, v222, v135
	v_sub_f32_e32 v193, v135, v89
	v_exp_f32_e32 v151, v151
	v_mov_b32_e32 v222, v135
	v_mfma_f32_16x16x32_bf16 v[20:23], v[90:93], v[224:227], v[20:23]
	v_sub_f32_e32 v114, v114, v192
	v_sub_f32_e32 v115, v115, v192
	v_sub_f32_e32 v116, v116, v192
	v_sub_f32_e32 v117, v117, v192
	v_sub_f32_e32 v118, v118, v192
	v_mfma_f32_16x16x32_bf16 v[4:7], v[90:93], v[232:235], v[4:7]
	v_sub_f32_e32 v119, v119, v192
	v_sub_f32_e32 v120, v120, v192
	v_sub_f32_e32 v121, v121, v192
	v_sub_f32_e32 v122, v122, v193
	v_sub_f32_e32 v123, v123, v193
	v_mfma_f32_16x16x32_bf16 v[16:19], v[94:97], v[224:227], v[16:19]
	v_sub_f32_e32 v124, v124, v193
	v_sub_f32_e32 v125, v125, v193
	v_sub_f32_e32 v126, v126, v193
	v_sub_f32_e32 v127, v127, v193
	v_sub_f32_e32 v128, v128, v193
	v_mfma_f32_16x16x32_bf16 v[0:3], v[94:97], v[232:235], v[0:3]
	v_sub_f32_e32 v129, v129, v193
	v_exp_f32_e32 v114, v114
	v_exp_f32_e32 v115, v115
	v_exp_f32_e32 v116, v116
	ds_read_b64 v[80:81], v236 offset:8192
	ds_read_b64 v[82:83], v237 offset:8192
	ds_read_b64 v[84:85], v236 offset:10240
	ds_read_b64 v[86:87], v237 offset:10240
	ds_read_b64 v[90:91], v236 offset:12288
	ds_read_b64 v[92:93], v237 offset:12288
	ds_read_b64 v[94:95], v236 offset:14336
	ds_read_b64 v[96:97], v237 offset:14336
	s_waitcnt lgkmcnt(8)
	v_mfma_f32_16x16x32_bf16 v[224:227], v[64:67], v[98:101], 0
	v_exp_f32_e32 v117, v117
	v_exp_f32_e32 v118, v118
	v_exp_f32_e32 v119, v119
	v_exp_f32_e32 v120, v120
	v_exp_f32_e32 v121, v121
	v_mfma_f32_16x16x32_bf16 v[228:231], v[68:71], v[98:101], 0
	v_exp_f32_e32 v122, v122
	v_exp_f32_e32 v123, v123
	v_exp_f32_e32 v124, v124
	v_exp_f32_e32 v125, v125
	v_exp_f32_e32 v126, v126
	v_mfma_f32_16x16x32_bf16 v[232:235], v[64:67], v[106:109], 0
	v_exp_f32_e32 v127, v127
	v_exp_f32_e32 v128, v128
	v_exp_f32_e32 v129, v129
	v_add_f32_e32 v134, v114, v115
	v_add_f32_e32 v188, v116, v117
	v_mfma_f32_16x16x32_bf16 v[130:133], v[68:71], v[106:109], 0
	v_add_f32_e32 v134, v134, v188
	v_add_f32_e32 v188, v118, v119
	v_add_f32_e32 v134, v134, v188
	v_add_f32_e32 v188, v120, v121
	v_add_f32_e32 v134, v134, v188
	v_mfma_f32_16x16x32_bf16 v[224:227], v[72:75], v[102:105], v[224:227]
	v_fma_f32 v185, v185, v190, v134
	v_add_f32_e32 v135, v122, v123
	v_add_f32_e32 v189, v124, v125
	v_add_f32_e32 v135, v135, v189
	v_add_f32_e32 v189, v126, v127
	v_mfma_f32_16x16x32_bf16 v[228:231], v[76:79], v[102:105], v[228:231]
	v_add_f32_e32 v135, v135, v189
	v_add_f32_e32 v189, v128, v129
	v_add_f32_e32 v135, v135, v189
	v_fma_f32 v184, v184, v151, v135
	v_cvt_pk_bf16_f32 v114, v114, v115
	v_mfma_f32_16x16x32_bf16 v[232:235], v[72:75], v[110:113], v[232:235]
	v_cvt_pk_bf16_f32 v115, v116, v117
	v_cvt_pk_bf16_f32 v116, v118, v119
	v_cvt_pk_bf16_f32 v117, v120, v121
	v_cvt_pk_bf16_f32 v122, v122, v123
	v_cvt_pk_bf16_f32 v123, v124, v125
	v_mfma_f32_16x16x32_bf16 v[130:133], v[76:79], v[110:113], v[130:133]
	v_cvt_pk_bf16_f32 v124, v126, v127
	v_cvt_pk_bf16_f32 v125, v128, v129
	v_cmp_neq_f32_e32 vcc, 1.0, v190
	s_nop 1
	s_cbranch_vccz .Lself_r4
	v_mul_f32_e32 v60, v60, v190
	v_mul_f32_e32 v61, v61, v190
	v_mul_f32_e32 v62, v62, v190
	v_mul_f32_e32 v63, v63, v190
	v_mul_f32_e32 v56, v56, v190
	v_mul_f32_e32 v57, v57, v190
	v_mul_f32_e32 v58, v58, v190
	v_mul_f32_e32 v59, v59, v190
	v_mul_f32_e32 v52, v52, v190
	v_mul_f32_e32 v53, v53, v190
	v_mul_f32_e32 v54, v54, v190
	v_mul_f32_e32 v55, v55, v190
	v_mul_f32_e32 v48, v48, v190
	v_mul_f32_e32 v49, v49, v190
	v_mul_f32_e32 v50, v50, v190
	v_mul_f32_e32 v51, v51, v190

.Lself_r5:
	s_waitcnt lgkmcnt(0)
	v_mfma_f32_16x16x32_bf16 v[60:63], v[80:83], v[114:117], v[60:63]
	v_max3_f32 v134, v224, s75, v225
	v_max3_f32 v134, v134, v226, v227
	v_max3_f32 v134, v134, v228, v229
	v_max3_f32 v134, v134, v230, v231
	v_max3_f32 v135, v232, s75, v233
	v_max3_f32 v135, v135, v234, v235
	v_max3_f32 v135, v135, v130, v131
	v_max3_f32 v135, v135, v132, v133
	v_add_f32_e32 v134, v134, v89
	v_add_f32_e32 v135, v135, v89
	v_mov_b32_e32 v188, v134
	v_mov_b32_e32 v189, v135
	s_nop 1
	v_permlane16_swap_b32_e32 v134, v188
	v_permlane16_swap_b32_e32 v135, v189
	v_max_f32_e32 v134, v134, v188
	v_max_f32_e32 v135, v135, v189
	v_mov_b32_e32 v188, v134
	v_mov_b32_e32 v189, v135
	s_nop 1
	v_permlane32_swap_b32_e32 v134, v188
	v_permlane32_swap_b32_e32 v135, v189
	v_mfma_f32_16x16x32_bf16 v[44:47], v[80:83], v[122:125], v[44:47]
	v_max3_f32 v134, v191, v134, v188
	v_sub_f32_e32 v190, v191, v134
	v_sub_f32_e32 v192, v134, v89
	v_exp_f32_e32 v190, v190
	v_mov_b32_e32 v191, v134
	v_max3_f32 v135, v171, v135, v189
	v_sub_f32_e32 v151, v171, v135
	v_sub_f32_e32 v193, v135, v89
	v_exp_f32_e32 v151, v151
	v_mov_b32_e32 v171, v135
	v_mfma_f32_16x16x32_bf16 v[56:59], v[84:87], v[114:117], v[56:59]
	v_sub_f32_e32 v224, v224, v192
	v_sub_f32_e32 v225, v225, v192
	v_sub_f32_e32 v226, v226, v192
	v_sub_f32_e32 v227, v227, v192
	v_sub_f32_e32 v228, v228, v192
	v_sub_f32_e32 v229, v229, v192
	v_sub_f32_e32 v230, v230, v192
	v_sub_f32_e32 v231, v231, v192
	v_sub_f32_e32 v232, v232, v193
	v_sub_f32_e32 v233, v233, v193
	v_mfma_f32_16x16x32_bf16 v[28:31], v[84:87], v[122:125], v[28:31]
	v_sub_f32_e32 v234, v234, v193
	v_sub_f32_e32 v235, v235, v193
	v_sub_f32_e32 v130, v130, v193
	v_sub_f32_e32 v131, v131, v193
	v_sub_f32_e32 v132, v132, v193
	v_sub_f32_e32 v133, v133, v193
	v_exp_f32_e32 v224, v224
	v_exp_f32_e32 v225, v225
	v_exp_f32_e32 v226, v226
	v_mfma_f32_16x16x32_bf16 v[52:55], v[90:93], v[114:117], v[52:55]
	v_exp_f32_e32 v227, v227
	v_exp_f32_e32 v228, v228
	v_exp_f32_e32 v229, v229
	v_exp_f32_e32 v230, v230
	v_exp_f32_e32 v231, v231
	v_exp_f32_e32 v232, v232
	v_exp_f32_e32 v233, v233
	v_exp_f32_e32 v234, v234
	v_exp_f32_e32 v235, v235
	v_exp_f32_e32 v130, v130
	v_mfma_f32_16x16x32_bf16 v[32:35], v[90:93], v[122:125], v[32:35]
	v_exp_f32_e32 v131, v131
	v_exp_f32_e32 v132, v132
	v_exp_f32_e32 v133, v133
	v_add_f32_e32 v134, v224, v225
	v_add_f32_e32 v188, v226, v227
	v_add_f32_e32 v134, v134, v188
	v_add_f32_e32 v188, v228, v229
	v_add_f32_e32 v134, v134, v188
	v_add_f32_e32 v188, v230, v231
	v_add_f32_e32 v134, v134, v188
	v_mfma_f32_16x16x32_bf16 v[48:51], v[94:97], v[114:117], v[48:51]
	v_fma_f32 v187, v187, v190, v134
	v_add_f32_e32 v135, v232, v233
	v_add_f32_e32 v189, v234, v235
	v_add_f32_e32 v135, v135, v189
	v_add_f32_e32 v189, v130, v131
	v_add_f32_e32 v135, v135, v189
	v_add_f32_e32 v189, v132, v133
	v_add_f32_e32 v135, v135, v189
	v_fma_f32 v186, v186, v151, v135
	v_cvt_pk_bf16_f32 v224, v224, v225
	v_mfma_f32_16x16x32_bf16 v[24:27], v[94:97], v[122:125], v[24:27]
	v_cvt_pk_bf16_f32 v225, v226, v227
	v_cvt_pk_bf16_f32 v226, v228, v229
	v_cvt_pk_bf16_f32 v227, v230, v231
	v_cvt_pk_bf16_f32 v232, v232, v233
	v_cvt_pk_bf16_f32 v233, v234, v235
	v_cvt_pk_bf16_f32 v234, v130, v131
	v_cvt_pk_bf16_f32 v235, v132, v133
	v_cmp_neq_f32_e32 vcc, 1.0, v190
	s_nop 1
	s_cbranch_vccz .Lself_r6
	v_mul_f32_e32 v40, v40, v190
	v_mul_f32_e32 v41, v41, v190
	v_mul_f32_e32 v42, v42, v190
	v_mul_f32_e32 v43, v43, v190
	v_mul_f32_e32 v36, v36, v190
	v_mul_f32_e32 v37, v37, v190
	v_mul_f32_e32 v38, v38, v190
	v_mul_f32_e32 v39, v39, v190
	v_mul_f32_e32 v20, v20, v190
	v_mul_f32_e32 v21, v21, v190
	v_mul_f32_e32 v22, v22, v190
	v_mul_f32_e32 v23, v23, v190
	v_mul_f32_e32 v16, v16, v190
	v_mul_f32_e32 v17, v17, v190
	v_mul_f32_e32 v18, v18, v190
	v_mul_f32_e32 v19, v19, v190

.Lself_r7:
	v_mfma_f32_16x16x32_bf16 v[40:43], v[80:83], v[224:227], v[40:43]
	v_mfma_f32_16x16x32_bf16 v[12:15], v[80:83], v[232:235], v[12:15]
	v_mfma_f32_16x16x32_bf16 v[36:39], v[84:87], v[224:227], v[36:39]
	v_mfma_f32_16x16x32_bf16 v[8:11], v[84:87], v[232:235], v[8:11]
	v_mfma_f32_16x16x32_bf16 v[20:23], v[90:93], v[224:227], v[20:23]
	v_mfma_f32_16x16x32_bf16 v[4:7], v[90:93], v[232:235], v[4:7]
	v_mfma_f32_16x16x32_bf16 v[16:19], v[94:97], v[224:227], v[16:19]
	v_mfma_f32_16x16x32_bf16 v[0:3], v[94:97], v[232:235], v[0:3]
	s_waitcnt lgkmcnt(0)
	s_waitcnt vmcnt(0)
	s_barrier
	s_andn2_b64 vcc, exec, s[4:5]
	s_cmp_lg_u64 s[6:7], 0
	s_cselect_b32 s6, 1, 0
	s_xor_b32 s42, s42, s6
	s_cbranch_vccz .LBB0_107
	s_branch .Lself_latch

	.amdhsa_kernel _Z10fwd_kernel6Paramsii
		.amdhsa_group_segment_fixed_size 73984
		.amdhsa_private_segment_fixed_size 0
		.amdhsa_kernarg_size 416
		.amdhsa_user_sgpr_count 2
		.amdhsa_user_sgpr_dispatch_ptr 0
		.amdhsa_user_sgpr_queue_ptr 0
		.amdhsa_user_sgpr_kernarg_segment_ptr 1
		.amdhsa_user_sgpr_dispatch_id 0
		.amdhsa_user_sgpr_kernarg_preload_length 0
		.amdhsa_user_sgpr_kernarg_preload_offset 0
		.amdhsa_user_sgpr_private_segment_size 0
		.amdhsa_uses_dynamic_stack 0
		.amdhsa_enable_private_segment 0
		.amdhsa_system_sgpr_workgroup_id_x 1
		.amdhsa_system_sgpr_workgroup_id_y 0
		.amdhsa_system_sgpr_workgroup_id_z 0
		.amdhsa_system_sgpr_workgroup_info 0
		.amdhsa_system_vgpr_workitem_id 2
		.amdhsa_next_free_vgpr 256
		.amdhsa_next_free_sgpr 100
		.amdhsa_accum_offset 256
		.amdhsa_reserve_vcc 1
		.amdhsa_float_round_mode_32 0
		.amdhsa_float_round_mode_16_64 0
		.amdhsa_float_denorm_mode_32 3
		.amdhsa_float_denorm_mode_16_64 3
		.amdhsa_dx10_clamp 1
		.amdhsa_ieee_mode 1
		.amdhsa_fp16_overflow 0
		.amdhsa_tg_split 0
		.amdhsa_exception_fp_ieee_invalid_op 0
		.amdhsa_exception_fp_denorm_src 0
		.amdhsa_exception_fp_ieee_div_zero 0
		.amdhsa_exception_fp_ieee_overflow 0
		.amdhsa_exception_fp_ieee_underflow 0
		.amdhsa_exception_fp_ieee_inexact 0
		.amdhsa_exception_int_div_zero 0
	.end_amdhsa_kernel

amdhsa.kernels:
  - .agpr_count:     0
    .args:
      - .offset:         0
        .size:           152
        .value_kind:     by_value
      - .offset:         152
        .size:           4
        .value_kind:     by_value
      - .offset:         156
        .size:           4
        .value_kind:     by_value
      - .offset:         160
        .size:           4
        .value_kind:     hidden_block_count_x
      - .offset:         164
        .size:           4
        .value_kind:     hidden_block_count_y
      - .offset:         168
        .size:           4
        .value_kind:     hidden_block_count_z
      - .offset:         172
        .size:           2
        .value_kind:     hidden_group_size_x
      - .offset:         174
        .size:           2
        .value_kind:     hidden_group_size_y
      - .offset:         176
        .size:           2
        .value_kind:     hidden_group_size_z
      - .offset:         178
        .size:           2
        .value_kind:     hidden_remainder_x
      - .offset:         180
        .size:           2
        .value_kind:     hidden_remainder_y
      - .offset:         182
        .size:           2
        .value_kind:     hidden_remainder_z
      - .offset:         200
        .size:           8
        .value_kind:     hidden_global_offset_x
      - .offset:         208
        .size:           8
        .value_kind:     hidden_global_offset_y
      - .offset:         216
        .size:           8
        .value_kind:     hidden_global_offset_z
      - .offset:         224
        .size:           2
        .value_kind:     hidden_grid_dims
      - .offset:         248
        .size:           8
        .value_kind:     hidden_multigrid_sync_arg
    .group_segment_fixed_size: 73984
    .kernarg_segment_align: 8
    .kernarg_segment_size: 416
    .language:       OpenCL C
    .language_version:
      - 2
      - 0
    .max_flat_workgroup_size: 256
    .name:           _Z10fwd_kernel6Paramsii
    .private_segment_fixed_size: 0
    .sgpr_count:     106
    .sgpr_spill_count: 111
    .symbol:         _Z10fwd_kernel6Paramsii.kd
    .uniform_work_group_size: 1
    .uses_dynamic_stack: false
    .vgpr_count:     256
    .vgpr_spill_count: 0
    .wavefront_size: 64
